# P0: per-job workgroup rotation so no workgroup converts more than 8 tiles
# speedup vs baseline: 1.0096x; 1.0096x over previous
; DEVINL void tr_job(const float* src, int K, int N, int Npad, u16* dst, int bid, int nb) {
;   const int tk = K / 64, tn = Npad / 256;
;   for (int t = bid; t < tk * tn; t += nb) {
;     int kt = t % tk, ntile = t / tk;
;     tr_tile(src, N, N, kt * 64, ntile * 256, dst, K, 1 << 30, 0, 0);
;   }
; }
; DEVINL void phase0(const Params& p) {
;     ...
;   tr_job(p.w_in, 2048, NC, NCP, (u16*)(ws + O_WINT), bid, nb);
;   tr_job(p.w_up_gla, 1024, 2048, 2048, (u16*)(ws + O_WUPGT), bid, nb);
.LBB0_39:
	s_add_u32 s30, s92, 0x1e500000
	s_addc_u32 s31, s93, 0
	s_add_u32 s2, s2, 0xc0
	s_and_b32 s2, s2, 0xff
	s_cmpk_gt_i32 s2, 0x7f
	s_cbranch_scc1 .Lp0_j3
	s_lshl_b32 s3, s2, 6
	s_lshl_b32 s6, s94, 6
	s_movk_i32 s4, 0x800
	s_movk_i32 s5, 0x404
	v_mov_b32_e32 v33, 0
	s_mov_b32 s7, s3
	s_mov_b32 s8, s2
	s_branch .LBB0_42

; DEVINL void tr_job(const float* src, int K, int N, int Npad, u16* dst, int bid, int nb) {
;   const int tk = K / 64, tn = Npad / 256;
;   for (int t = bid; t < tk * tn; t += nb) {
;     int kt = t % tk, ntile = t / tk;
;     tr_tile(src, N, N, kt * 64, ntile * 256, dst, K, 1 << 30, 0, 0);
;   }
; }
; DEVINL void phase0(const Params& p) {
;     ...
;   tr_job(p.w_up_gla, 1024, 2048, 2048, (u16*)(ws + O_WUPGT), bid, nb);
;   tr_job(p.w_up_rwkv, 1024, 2048, 2048, (u16*)(ws + O_WUPRT), bid, nb);
.LBB0_58:
.Lp0_j3:
	s_add_u32 s2, s2, 0x80
	s_and_b32 s2, s2, 0xff
	s_lshl_b32 s3, s2, 6
	s_lshl_b32 s6, s94, 6
	s_cmpk_gt_i32 s2, 0x7f
	s_cbranch_scc1 .LBB0_76
	s_add_u32 s4, s92, 0x1e900000
	s_addc_u32 s5, s93, 0
	s_movk_i32 s7, 0x800
	s_movk_i32 s8, 0x404
	v_mov_b32_e32 v33, 0
	s_mov_b32 s9, s2
	s_branch .LBB0_60

; DEVINL void tr_job(const float* src, int K, int N, int Npad, u16* dst, int bid, int nb) {
;   const int tk = K / 64, tn = Npad / 256;
;   for (int t = bid; t < tk * tn; t += nb) {
;     int kt = t % tk, ntile = t / tk;
;     tr_tile(src, N, N, kt * 64, ntile * 256, dst, K, 1 << 30, 0, 0);
;   }
; }
; DEVINL void phase0(const Params& p) {
;     ...
;   tr_job(p.w_up_rwkv, 1024, 2048, 2048, (u16*)(ws + O_WUPRT), bid, nb);
;   tr_job(p.w_out, 2048, 2048, 2048, (u16*)(ws + O_WOUTT), bid, nb);
.LBB0_76:
	s_add_u32 s2, s2, 0xc0
	s_and_b32 s2, s2, 0xff
	s_add_u32 s28, s92, 0x1ed00000
	s_addc_u32 s29, s93, 0
	s_cmpk_lt_i32 s2, 0x100
	s_cselect_b64 s[0:1], -1, 0
	v_writelane_b32 v254, s0, 18
	s_cmpk_gt_i32 s2, 0xff
	s_nop 0
	v_writelane_b32 v254, s1, 19
	s_cbranch_scc1 .LBB0_95
	s_lshl_b32 s3, s2, 6
	s_lshl_b32 s4, s94, 6
	s_movk_i32 s5, 0x800
	s_movk_i32 s6, 0x404
	v_mov_b32_e32 v33, 0
	s_mov_b32 s7, s2
	s_branch .LBB0_79

; DEVINL void tr_job(const float* src, int K, int N, int Npad, u16* dst, int bid, int nb) {
;   const int tk = K / 64, tn = Npad / 256;
;   for (int t = bid; t < tk * tn; t += nb) {
;     int kt = t % tk, ntile = t / tk;
;     tr_tile(src, N, N, kt * 64, ntile * 256, dst, K, 1 << 30, 0, 0);
;   }
; }
; DEVINL void phase0(const Params& p) {
;     ...
;   tr_job(p.w_out, 2048, 2048, 2048, (u16*)(ws + O_WOUTT), bid, nb);
;   tr_job(p.rw_w_up_f, 64, 1024, 1024, (u16*)(ws + O_LWF), bid, nb);
.LBB0_95:
	s_add_u32 s10, s92, 0x1f500000
	s_addc_u32 s11, s93, 0
	s_add_u32 s2, s2, 0xc0
	s_and_b32 s2, s2, 0xff
	s_cmp_gt_i32 s2, 3
	s_cbranch_scc1 .Lp0_j6
	s_lshl_b32 s3, s2, 8
	s_lshl_b32 s6, s94, 8
	s_movk_i32 s4, 0x400
	s_movk_i32 s5, 0x404
	v_mov_b32_e32 v33, 0
	s_mov_b32 s7, s3
	s_mov_b32 s8, s2
	s_branch .LBB0_98

; DEVINL void tr_job(const float* src, int K, int N, int Npad, u16* dst, int bid, int nb) {
;   const int tk = K / 64, tn = Npad / 256;
;   for (int t = bid; t < tk * tn; t += nb) {
;     int kt = t % tk, ntile = t / tk;
;     tr_tile(src, N, N, kt * 64, ntile * 256, dst, K, 1 << 30, 0, 0);
;   }
; }
; DEVINL void phase0(const Params& p) {
;     ...
;   tr_job(p.rw_w_up_f, 64, 1024, 1024, (u16*)(ws + O_LWF), bid, nb);
;   tr_job(p.rw_w_up_b, 64, 1024, 1024, (u16*)(ws + O_LWB), bid, nb);
.LBB0_114:
.Lp0_j6:
	s_add_u32 s2, s2, 0xfc
	s_and_b32 s2, s2, 0xff
	s_lshl_b32 s3, s2, 8
	s_lshl_b32 s6, s94, 8
	s_cmp_gt_i32 s2, 3
	s_cbranch_scc1 .Lp0_j7
	s_add_u32 s4, s92, 0x1f520000
	s_addc_u32 s5, s93, 0
	s_movk_i32 s7, 0x400
	s_movk_i32 s8, 0x404
	v_mov_b32_e32 v33, 0
	s_mov_b32 s9, s3
	s_mov_b32 s14, s2
	s_branch .LBB0_116

; DEVINL void tr_job(const float* src, int K, int N, int Npad, u16* dst, int bid, int nb) {
;   const int tk = K / 64, tn = Npad / 256;
;   for (int t = bid; t < tk * tn; t += nb) {
;     int kt = t % tk, ntile = t / tk;
;     tr_tile(src, N, N, kt * 64, ntile * 256, dst, K, 1 << 30, 0, 0);
;   }
; }
; DEVINL void phase0(const Params& p) {
;     ...
;   tr_job(p.rw_w_up_b, 64, 1024, 1024, (u16*)(ws + O_LWB), bid, nb);
;   tr_job(p.rw_a_up, 64, 1024, 1024, (u16*)(ws + O_LA), bid, nb);
.LBB0_132:
.Lp0_j7:
	s_add_u32 s2, s2, 0xfc
	s_and_b32 s2, s2, 0xff
	s_lshl_b32 s3, s2, 8
	s_lshl_b32 s6, s94, 8
	s_cmp_gt_i32 s2, 3
	s_cbranch_scc1 .LBB0_150
	s_add_u32 s4, s92, 0x1f540000
	s_addc_u32 s5, s93, 0
	s_movk_i32 s7, 0x400
	s_movk_i32 s8, 0x404
	v_mov_b32_e32 v33, 0
	s_mov_b32 s9, s2
	s_branch .LBB0_134

; DEVINL void tr_job(const float* src, int K, int N, int Npad, u16* dst, int bid, int nb) {
;   const int tk = K / 64, tn = Npad / 256;
;   for (int t = bid; t < tk * tn; t += nb) {
;     int kt = t % tk, ntile = t / tk;
;     tr_tile(src, N, N, kt * 64, ntile * 256, dst, K, 1 << 30, 0, 0);
;   }
; }
; DEVINL void phase0(const Params& p) {
;     ...
;   tr_job(p.rw_a_up, 64, 1024, 1024, (u16*)(ws + O_LA), bid, nb);
;   tr_job(p.rw_g_up, 128, 1024, 1024, (u16*)(ws + O_LG), bid, nb);
.LBB0_150:
	s_add_u32 s2, s2, 0xfc
	s_and_b32 s2, s2, 0xff
	s_waitcnt lgkmcnt(0)
	s_add_u32 s14, s92, 0x1f560000
	s_addc_u32 s15, s93, 0
	s_cmp_gt_i32 s2, 7
	s_cbranch_scc1 .LBB0_169
	s_lshl_b32 s3, s2, 6
	s_lshl_b32 s4, s94, 6
	s_movk_i32 s5, 0x400
	s_movk_i32 s6, 0x404
	v_mov_b32_e32 v33, 0
	s_mov_b32 s7, s2
	s_branch .LBB0_153

; DEVINL void xcd_barrier(const XcdBarrier& b) {
;   asm volatile("s_waitcnt vmcnt(0)" ::: "memory");
;   __syncthreads();
;   if (threadIdx.x == 0) {
;     unsigned* bar = b.bar;
;     __builtin_amdgcn_s_waitcnt(0);
;     unsigned nloc = b.st[0], nx = b.st[1];
;     if (nloc == 0u) { xcd_barrier_complete(bar, b.x, nloc, nx); b.st[0] = nloc; b.st[1] = nx; }
.LBB0_169:
	s_add_u32 s2, s2, 0x4c
	s_and_b32 s2, s2, 0xff
	s_waitcnt vmcnt(0)
	s_barrier
	s_mov_b64 s[4:5], exec
	v_readlane_b32 s0, v254, 0
	v_readlane_b32 s1, v254, 1
	s_and_b64 s[0:1], s[4:5], s[0:1]
	s_mov_b64 exec, s[0:1]
	s_cbranch_execz .LBB0_221
	v_mov_b32_e32 v0, 0
	s_waitcnt vmcnt(0) expcnt(0) lgkmcnt(0)
	ds_read_b32 v2, v0
	ds_read_b32 v1, v0 offset:4
	s_waitcnt lgkmcnt(1)
	v_cmp_ne_u32_e32 vcc, 0, v2
	s_cbranch_vccnz .LBB0_185
	s_add_u32 s8, s92, 0x217c0200
	s_addc_u32 s9, s93, 0
	s_add_u32 s18, s92, 0x217c0400
	s_addc_u32 s19, s93, 0
	s_add_u32 s22, s92, 0x217c0500
	s_addc_u32 s23, s93, 0
	s_add_u32 s24, s92, 0x217c0600
	s_addc_u32 s25, s93, 0
	s_add_u32 s36, s92, 0x217c0700
	s_addc_u32 s37, s93, 0
	s_add_u32 s38, s92, 0x217c0800
	s_addc_u32 s39, s93, 0
	s_add_u32 s68, s92, 0x217c0900
	s_addc_u32 s69, s93, 0
	s_add_u32 s70, s92, 0x217c0a00
	s_addc_u32 s71, s93, 0
	s_add_u32 s72, s92, 0x217c0b00
	s_addc_u32 s73, s93, 0
	s_add_u32 s78, s92, 0x217c0c00
	s_addc_u32 s79, s93, 0
	s_mov_b64 s[56:57], s[96:97]
	s_add_u32 s96, s92, 0x217c0d00
	s_addc_u32 s97, s93, 0
	s_add_u32 s6, s92, 0x217c0e00
	s_addc_u32 s7, s93, 0
	s_add_u32 s40, s92, 0x217c0f00
	s_addc_u32 s41, s93, 0
	s_add_u32 s42, s92, 0x217c1000
	s_addc_u32 s43, s93, 0
	s_add_u32 s0, s92, 0x217c1100
	s_addc_u32 s1, s93, 0
	s_add_u32 s44, s92, 0x217c1200
	s_addc_u32 s45, s93, 0
	s_mul_i32 s3, s95, s54
	s_add_u32 s46, s92, 0x217c1300
	s_mul_i32 s3, s3, s94
	s_addc_u32 s47, s93, 0
	s_mov_b32 s55, 1
	s_branch .LBB0_173
